# norm rewrite, SSD S2 hand schedule + LDS swizzle + XCD item map, attention K/V load hoist (scratch SGPR fix)
# speedup vs baseline: 1.0264x; 1.0002x over previous
; __device__ __forceinline__ void attn_item(const Args& a, LAS unsigned char* lds, int layer, bool is_sample, int b, int c, int kvh, int seq_row0, int nchunks, bf16_t* proj, const int tid) {
;     ...
;     u32x4 qraw[2][2];
;     {
;         const int hq_ = kvh * 4 + (wave >> 1);
; #pragma unroll
;         for (int sub = 0; sub < 2; ++sub) { const bf16_t* qp_ = proj + (size_t)(row0 + (wave & 1) * 32 + sub * 16 + fr) * PN + C_Q + hq_ * 64;
; #pragma unroll
;             for (int ks = 0; ks < 2; ++ks) qraw[sub][ks] = *(const u32x4*)(qp_ + 32 * ks + 8 * fq); }
;     }
; #pragma unroll
;     for (int i = 0; i < 3; ++i) {
;         const int slot = tid + 512 * i, kl = slot >> 3, oc = slot & 7;
;         const int pos = c * 64 - 128 + kl;
;         float kf[8], vf[8];
;         if (is_sample && kl < 128) {
;             const size_t off = (((size_t)(layer * NSB + b) * 128 + kl) * NKVH + kvh) * 64 + oc * 8;
;             const f32x4 k0 = *(const f32x4*)(a.in[2] + off), k1 = *(const f32x4*)(a.in[2] + off + 4), v0 = *(const f32x4*)(a.in[3] + off), v1 = *(const f32x4*)(a.in[3] + off + 4);
; #pragma unroll
;             for (int e = 0; e < 4; ++e) { kf[e] = k0[e]; kf[4 + e] = k1[e]; vf[e] = v0[e]; vf[4 + e] = v1[e]; }
;         } else if (pos >= 0) {
;             const bf16_t* rp = proj + (size_t)(seq_row0 + pos) * PN;
;             const u32x4 kw = *(const u32x4*)(rp + C_K + kvh * 64 + oc * 8), vw = *(const u32x4*)(rp + C_V + kvh * 64 + oc * 8);
.LBB0_454:
	s_and_b64 vcc, exec, s[4:5]
	s_cbranch_vccz .LBB0_482
	s_ashr_i32 s4, s16, 7
	v_readlane_b32 s5, v255, 38
	s_add_i32 s6, s4, s5
	v_mov_b32_e32 v36, v166
	s_lshl_b32 s4, s6, 11
	v_readlane_b32 s5, v255, 31
	s_and_b32 s7, s3, 3
	s_bfe_u32 s21, s3, 0x50002
	s_sub_i32 s43, s4, s5
	v_readfirstlane_b32 s4, v36
	v_and_b32_e32 v41, 15, v36
	s_lshl_b32 s38, s21, 6
	s_lshl_b32 s40, s7, 2
	s_ashr_i32 s20, s4, 7
	s_lshr_b32 s4, s4, 1
	s_or_b32 s23, s43, s38
	s_add_i32 s39, s20, s40
	v_and_or_b32 v92, s4, 32, v41
	v_or_b32_e32 v12, s23, v92
	s_lshl_b32 s8, s39, 6
	v_mov_b64_e32 v[10:11], s[18:19]
	s_ashr_i32 s9, s8, 31
	v_mad_i64_i32 v[2:3], s[4:5], v12, s33, v[10:11]
	v_bfe_u32 v42, v36, 4, 2
	s_lshl_b64 s[4:5], s[8:9], 1
	v_lshl_add_u64 v[2:3], v[2:3], 0, s[4:5]
	v_lshlrev_b32_e32 v0, 4, v42
	v_or_b32_e32 v12, 16, v12
	v_lshl_add_u64 v[2:3], v[2:3], 0, v[0:1]
	s_mov_b64 s[16:17], 0x2800
	s_movk_i32 s10, 0x2000
	v_mad_i64_i32 v[10:11], s[14:15], v12, s33, v[10:11]
	v_lshl_add_u64 v[6:7], v[2:3], 0, s[16:17]
	v_add_co_u32_e32 v2, vcc, s10, v2
	v_lshl_add_u64 v[10:11], v[10:11], 0, s[4:5]
	s_nop 0
	v_addc_co_u32_e32 v3, vcc, 0, v3, vcc
	v_lshl_add_u64 v[10:11], v[10:11], 0, v[0:1]
	v_lshl_add_u64 v[14:15], v[10:11], 0, s[16:17]
	v_add_co_u32_e32 v10, vcc, s10, v10
	global_load_dwordx4 v[2:5], v[2:3], off offset:2048
	s_nop 0
	global_load_dwordx4 v[6:9], v[6:7], off offset:64
	v_addc_co_u32_e32 v11, vcc, 0, v11, vcc
	global_load_dwordx4 v[10:13], v[10:11], off offset:2048
	s_nop 0
	global_load_dwordx4 v[14:17], v[14:15], off offset:64
	v_and_b32_e32 v19, 7, v36
	s_add_i32 s44, s38, 0xffffff80
	s_lshl_b32 s41, s7, 6
	v_readlane_b32 s4, v255, 14
	v_ashrrev_i32_e32 v37, 3, v36
	v_lshlrev_b32_e32 v43, 3, v19
	v_lshlrev_b32_e32 v0, 5, v19
	v_readlane_b32 s5, v255, 15
	s_cmp_lt_u32 s21, 30
	v_add_u32_e32 v40, s44, v37
	s_mov_b64 s[28:29], 0x2800
	s_movk_i32 s36, 0x2000
	v_lshl_add_u64 v[38:39], s[4:5], 0, v[0:1]
	s_cselect_b64 s[14:15], -1, 0
	s_or_b32 s42, s38, 0xfffff800
	s_ashr_i32 s7, s6, 31
	v_cmp_lt_i32_e32 vcc, -1, v40
	v_mov_b32_e32 v18, 0
	v_lshlrev_b32_e32 v0, 1, v43
	v_mov_b32_e32 v20, 0
	v_mov_b32_e32 v21, 0
	v_mov_b32_e32 v22, 0
	v_mov_b32_e32 v23, 0
	v_mov_b32_e32 v24, 0
	v_mov_b32_e32 v25, 0
	v_mov_b32_e32 v26, 0
	v_mov_b32_e32 v27, 0
	v_mov_b32_e32 v28, 0
	v_mov_b32_e32 v29, 0
	v_mov_b32_e32 v30, 0
	v_mov_b32_e32 v31, 0
	v_mov_b32_e32 v32, 0
	v_mov_b32_e32 v33, 0
	v_mov_b32_e32 v34, 0
	v_mov_b32_e32 v35, 0
	v_add_u32_e32 v244, s43, v40
	v_mov_b64_e32 v[240:241], s[18:19]
	v_mad_i64_i32 v[240:241], s[4:5], v244, s33, v[240:241]
	s_lshl_b32 s100, s41, 1
	s_mov_b32 s101, 0
	v_lshl_add_u64 v[240:241], v[240:241], 0, s[100:101]
	v_lshl_add_u64 v[240:241], v[240:241], 0, v[0:1]
	s_mov_b64 s[100:101], 0x11b000
	v_lshl_add_u64 v[242:243], v[240:241], 0, s[100:101]
	global_load_dwordx4 v[232:235], v[38:39], off
	global_load_dwordx4 v[236:239], v[38:39], off offset:16
	global_load_dwordx4 v[216:219], v[242:243], off
	global_load_dwordx4 v[220:223], v[242:243], off offset:512
	s_mov_b64 s[100:101], 0x233000
	v_lshl_add_u64 v[242:243], v[240:241], 0, s[100:101]
	global_load_dwordx4 v[224:227], v[242:243], off
	global_load_dwordx4 v[228:231], v[242:243], off offset:512
	s_and_saveexec_b64 s[16:17], vcc
	s_cbranch_execz .LBB0_459
; __device__ __forceinline__ float bflo(unsigned w) { return __uint_as_float(w << 16); }
; __device__ __forceinline__ float bfhi(unsigned w) { return __uint_as_float(w & 0xffff0000u); }
; __device__ __forceinline__ void attn_item(const Args& a, LAS unsigned char* lds, int layer, bool is_sample, int b, int c, int kvh, int seq_row0, int nchunks, bf16_t* proj, const int tid) {
;     ...
;         } else if (pos >= 0) {
;             const bf16_t* rp = proj + (size_t)(seq_row0 + pos) * PN;
;             const u32x4 kw = *(const u32x4*)(rp + C_K + kvh * 64 + oc * 8), vw = *(const u32x4*)(rp + C_V + kvh * 64 + oc * 8);
;             kf[0] = bflo(kw.x); kf[1] = bfhi(kw.x); kf[2] = bflo(kw.y); kf[3] = bfhi(kw.y); kf[4] = bflo(kw.z); kf[5] = bfhi(kw.z); kf[6] = bflo(kw.w); kf[7] = bfhi(kw.w);
;             vf[0] = bflo(vw.x); vf[1] = bfhi(vw.x); vf[2] = bflo(vw.y); vf[3] = bfhi(vw.y); vf[4] = bflo(vw.z); vf[5] = bfhi(vw.z); vf[6] = bflo(vw.w); vf[7] = bfhi(vw.w);
;             float ss = 0.f;
; #pragma unroll
;             for (int e = 0; e < 8; ++e) ss += kf[e] * kf[e];
;             ss += __shfl_xor(ss, 1); ss += __shfl_xor(ss, 2); ss += __shfl_xor(ss, 4);
;             const float rs = rsqrtf(ss * (1.f / 64.f) + EPS);
;             const f32x4 g0 = *(const f32x4*)(kng + oc * 8), g1 = *(const f32x4*)(kng + oc * 8 + 4);
; #pragma unroll
;             for (int e = 0; e < 4; ++e) { kf[e] = kf[e] * rs * g0[e]; kf[4 + e] = kf[4 + e] * rs * g1[e]; }
;             if (kl >= 128 && (is_sample || c >= nchunks - 2)) {
;                 const int orow = is_sample ? (kl - 128) : (c - (nchunks - 2)) * 64 + (kl - 128);
;                 const size_t nb_ = is_sample ? NSB : NPB; const int lr = is_sample ? DSEQ : 128;
;                 const size_t off = (((size_t)(layer * nb_ + b) * lr + orow) * NKVH + kvh) * 64 + oc * 8;
;                 float* ko = a.out + (is_sample ? O_KS : O_KP) + off; float* vo = a.out + (is_sample ? O_VS : O_VP) + off;
;                 *(f32x4*)ko = (f32x4){kf[0], kf[1], kf[2], kf[3]}; *(f32x4*)(ko + 4) = (f32x4){kf[4], kf[5], kf[6], kf[7]};
;                 *(f32x4*)vo = (f32x4){vf[0], vf[1], vf[2], vf[3]}; *(f32x4*)(vo + 4) = (f32x4){vf[4], vf[5], vf[6], vf[7]};
;             }
	v_add_u32_e32 v22, s43, v40
	v_mov_b64_e32 v[20:21], s[18:19]
	v_mad_i64_i32 v[20:21], s[4:5], v22, s33, v[20:21]
	s_lshl_b32 s10, s41, 1
	v_lshl_add_u64 v[20:21], v[20:21], 0, s[10:11]
	v_lshl_add_u64 v[20:21], v[20:21], 0, v[0:1]
	v_add_co_u32_e32 v24, vcc, 0x3000, v20
	s_movk_i32 s4, 0x7f
	s_nop 0
	v_addc_co_u32_e32 v25, vcc, 0, v21, vcc
	global_load_dwordx4 v[20:23], v[24:25], off
	s_nop 0
	global_load_dwordx4 v[24:27], v[24:25], off offset:512
	s_nop 0
	v_cmp_lt_i32_e32 vcc, v204, v203
	s_xor_b64 s[46:47], s[14:15], -1
	s_waitcnt vmcnt(1)
	v_mov_b32_e32 v28, v232
	v_mov_b32_e32 v29, v233
	v_mov_b32_e32 v30, v234
	v_mov_b32_e32 v31, v235
	v_mov_b32_e32 v32, v236
	v_mov_b32_e32 v33, v237
	v_mov_b32_e32 v34, v238
	v_mov_b32_e32 v35, v239
	v_lshlrev_b32_e32 v48, 16, v20
	v_and_b32_e32 v49, 0xffff0000, v20
	v_lshlrev_b32_e32 v50, 16, v21
	v_and_b32_e32 v51, 0xffff0000, v21
	v_pk_mul_f32 v[52:53], v[48:49], v[48:49]
	v_pk_mul_f32 v[54:55], v[50:51], v[50:51]
	v_add_f32_e32 v52, v52, v53
	v_lshlrev_b32_e32 v46, 16, v22
	v_and_b32_e32 v47, 0xffff0000, v22
	v_add_f32_e32 v52, v54, v52
	v_and_b32_e32 v44, 0xffff0000, v23
	v_lshlrev_b32_e32 v45, 16, v23
	v_pk_mul_f32 v[22:23], v[46:47], v[46:47]
	v_add_f32_e32 v52, v55, v52
	v_add_f32_e32 v22, v22, v52
	v_pk_mul_f32 v[20:21], v[44:45], v[44:45]
	v_add_f32_e32 v22, v23, v22
	v_cndmask_b32_e32 v40, v201, v204, vcc
	v_add_f32_e32 v21, v21, v22
	v_lshlrev_b32_e32 v40, 2, v40
	v_add_f32_e32 v20, v20, v21
	ds_bpermute_b32 v21, v40, v20
	v_cmp_lt_i32_e32 vcc, s4, v37
	v_cmp_lt_i32_e64 s[4:5], v205, v203
	s_and_b64 s[46:47], vcc, s[46:47]
	s_waitcnt lgkmcnt(0)
	v_add_f32_e32 v21, v20, v21
	v_cndmask_b32_e64 v22, v201, v205, s[4:5]
	v_lshlrev_b32_e32 v22, 2, v22
	ds_bpermute_b32 v22, v22, v21
	v_cmp_lt_i32_e64 s[4:5], v206, v203
	s_waitcnt lgkmcnt(0)
	v_add_f32_e32 v40, v21, v22
	v_cndmask_b32_e64 v20, v201, v206, s[4:5]
	v_lshlrev_b32_e32 v23, 2, v20
	ds_bpermute_b32 v52, v23, v40
	s_waitcnt vmcnt(0)
	v_lshlrev_b32_e32 v22, 16, v25
	v_and_b32_e32 v23, 0xffff0000, v25
	s_mov_b32 s4, 0x800000
	v_lshlrev_b32_e32 v20, 16, v24
	s_waitcnt lgkmcnt(0)
	v_add_f32_e32 v25, v40, v52
	v_fmamk_f32 v25, v25, 0x3c800000, v167
	v_mul_f32_e32 v40, 0x4b800000, v25
	v_cmp_gt_f32_e64 s[4:5], s4, v25
	v_and_b32_e32 v21, 0xffff0000, v24
	v_lshlrev_b32_e32 v24, 16, v26
	v_cndmask_b32_e64 v25, v25, v40, s[4:5]
	v_rsq_f32_e32 v40, v25
	v_and_b32_e32 v25, 0xffff0000, v26
	v_lshlrev_b32_e32 v26, 16, v27
	v_and_b32_e32 v27, 0xffff0000, v27
	v_mul_f32_e32 v52, 0x45800000, v40
	v_cndmask_b32_e64 v40, v40, v52, s[4:5]
	v_pk_mul_f32 v[48:49], v[40:41], v[48:49] op_sel_hi:[0,1]
	v_pk_mul_f32 v[46:47], v[40:41], v[46:47] op_sel_hi:[0,1]
	v_pk_mul_f32 v[50:51], v[40:41], v[50:51] op_sel_hi:[0,1]
	v_pk_mul_f32 v[44:45], v[40:41], v[44:45] op_sel_hi:[0,1]
	s_waitcnt vmcnt(1)
	v_pk_mul_f32 v[28:29], v[28:29], v[48:49]
	s_waitcnt vmcnt(0)
	v_pk_mul_f32 v[32:33], v[32:33], v[46:47]
	v_pk_mul_f32 v[30:31], v[30:31], v[50:51]
	v_pk_mul_f32 v[34:35], v[34:35], v[44:45] op_sel:[0,1] op_sel_hi:[1,0]
	s_and_saveexec_b64 s[4:5], s[46:47]
	s_cbranch_execz .LBB0_458
	s_lshl_b64 s[46:47], s[6:7], 7
	v_readlane_b32 s48, v255, 16
	v_add_u32_e32 v44, s42, v37
	v_readlane_b32 s49, v255, 17
	s_add_u32 s46, s46, s48
	s_addc_u32 s47, s47, s49
	v_ashrrev_i32_e32 v45, 31, v44
	v_lshl_add_u64 v[44:45], s[46:47], 0, v[44:45]
	v_lshlrev_b64 v[44:45], 8, v[44:45]
	v_or3_b32 v45, v45, 0, 0
	v_or3_b32 v44, v44, v43, s41
	v_readlane_b32 s46, v253, 58
	v_lshlrev_b64 v[44:45], 2, v[44:45]
	v_readlane_b32 s47, v253, 59
	s_nop 1
	v_lshl_add_u64 v[46:47], s[46:47], 0, v[44:45]
	v_readlane_b32 s46, v253, 60
	v_readlane_b32 s47, v253, 61
	s_nop 1
	v_lshl_add_u64 v[44:45], s[46:47], 0, v[44:45]
	global_store_dwordx4 v[46:47], v[28:31], off
	global_store_dwordx4 v[46:47], v[32:35], off offset:16
	global_store_dwordx4 v[44:45], v[20:23], off
	global_store_dwordx4 v[44:45], v[24:27], off offset:16
